# scan: the 16 threads that load b_last and publish the per-row decay moved from critical wave 0 to wave 4 (which has slack)
# baseline (speedup 1.0000x reference)
.LBB0_1144:
	s_ashr_i32 s5, s85, 2
	s_lshl_b32 s7, s85, 6
	s_lshl_b32 s6, s5, 8
	s_and_b32 s10, s7, 0x80
	s_or_b32 s6, s6, s10
	s_and_b32 s4, s85, 1
	s_bfe_i32 s8, s85, 0x10000
	s_ashr_i32 s12, s85, 4
	s_mul_hi_i32 s7, s6, 0x4200
	s_mulk_i32 s6, 0x4200
	s_and_b32 s11, s5, 3
	s_add_u32 s6, s56, s6
	s_addc_u32 s7, s57, s7
	s_cmp_eq_u32 s4, 0
	s_cselect_b64 s[4:5], -1, 0
	v_mov_b32_e32 v3, v148
	s_and_b64 s[14:15], s[4:5], exec
	s_mov_b32 s9, 0xc400000
	s_barrier
	s_cselect_b32 s9, s9, 0x10600000
	v_ashrrev_i32_e32 v14, 6, v3
	s_mov_b32 s13, 0x14800000
	v_add_u32_e32 v0, -4, v14
	s_cselect_b32 s13, s13, 0x1c800000
	s_cselect_b32 s86, 63, 0
	s_add_u32 s70, s54, s9
	v_lshrrev_b32_e32 v15, 1, v0
	v_and_b32_e32 v16, 1, v14
	s_addc_u32 s71, s55, 0
	v_cmp_gt_u32_e32 vcc, v16, v15
	s_add_u32 s13, s54, s13
	s_addc_u32 s14, s55, 0
	v_cndmask_b32_e64 v0, 0, 1, vcc
	v_cmp_lt_u32_e32 vcc, v16, v15
	s_lshl_b32 s87, s12, 8
	s_and_b32 s8, s8, 0xc0
	v_cndmask_b32_e64 v4, 0, 1, vcc
	s_add_i32 s87, s87, 0x10000
	v_cndmask_b32_e64 v17, v4, v0, s[4:5]
	s_or_b32 s15, s87, s8
	v_lshlrev_b32_e32 v4, 2, v3
	s_lshl_b32 s16, s8, 1
	s_or_b32 s8, s15, s86
	v_ashrrev_i32_e32 v149, 4, v3
	v_lshlrev_b32_e32 v0, 3, v3
	v_and_b32_e32 v21, 4, v4
	s_ashr_i32 s9, s8, 31
	v_and_b32_e32 v22, 0x78, v0
	v_add_u32_e32 v4, s15, v149
	v_ashrrev_i32_e32 v5, 31, v4
	v_lshl_or_b32 v136, s11, 7, v22
	s_lshl_b64 s[8:9], s[8:9], 10
	v_lshlrev_b64 v[4:5], 10, v[4:5]
	s_waitcnt vmcnt(11)
	v_lshlrev_b32_e32 v8, 1, v136
	s_add_u32 s8, s70, s8
	v_or_b32_e32 v4, v4, v8
	s_addc_u32 s9, s71, s9
	s_lshl_b32 s17, s11, 8
	v_add_u32_e32 v23, 0x200, v3
	s_waitcnt vmcnt(5)
	v_lshl_add_u64 v[6:7], s[76:77], 0, v[4:5]
	s_add_u32 s8, s8, s17
	v_ashrrev_i32_e32 v172, 4, v23
	s_addc_u32 s9, s9, 0
	v_lshlrev_b32_e32 v0, 1, v22
	global_load_dwordx4 v[138:141], v[6:7], off
	global_load_dwordx4 v[142:145], v0, s[8:9]
	v_add_u32_e32 v6, s15, v172
	v_ashrrev_i32_e32 v7, 31, v6
	v_lshlrev_b64 v[6:7], 10, v[6:7]
	v_lshl_add_u64 v[4:5], s[70:71], 0, v[4:5]
	v_or_b32_e32 v6, v6, v8
	v_lshl_add_u64 v[8:9], s[76:77], 0, v[6:7]
	global_load_dwordx4 v[156:159], v[4:5], off
	global_load_dwordx4 v[160:163], v[8:9], off
	v_lshl_add_u64 v[4:5], s[70:71], 0, v[6:7]
	global_load_dwordx4 v[164:167], v[4:5], off
	v_ashrrev_i32_e32 v12, 3, v3
	v_mov_b64_e32 v[4:5], s[6:7]
	v_mad_i64_i32 v[6:7], s[6:7], v12, s33, v[4:5]
	v_add_u32_e32 v12, 64, v12
	s_or_b32 s48, s16, 0x4000
	v_lshlrev_b32_e32 v24, 4, v3
	v_mad_i64_i32 v[4:5], s[6:7], v12, s33, v[4:5]
	v_lshl_add_u64 v[8:9], v[6:7], 0, s[48:49]
	v_and_b32_e32 v10, 0x70, v24
	v_mov_b32_e32 v11, v1
	v_lshl_add_u64 v[12:13], v[4:5], 0, s[48:49]
	v_lshl_add_u64 v[8:9], v[8:9], 0, v[10:11]
	v_lshl_add_u64 v[12:13], v[12:13], 0, v[10:11]
	global_load_dwordx4 v[128:131], v[8:9], off
	global_load_dwordx4 v[132:135], v[12:13], off
	v_ashrrev_i32_e32 v8, 7, v3
	v_lshlrev_b32_e32 v9, 1, v149
	v_lshrrev_b32_e32 v12, 1, v21
	v_and_b32_e32 v25, 14, v9
	v_lshlrev_b32_e32 v9, 7, v22
	v_xor_b32_e32 v13, v12, v8
	v_lshl_add_u32 v26, v13, 4, v9
	v_or_b32_e32 v13, 2, v22
	v_or_b32_e32 v29, 3, v22
	v_or_b32_e32 v32, 8, v22
	v_or_b32_e32 v35, 9, v22
	v_or_b32_e32 v38, 10, v22
	v_or_b32_e32 v22, 11, v22
	v_lshlrev_b32_e32 v27, 7, v13
	v_lshrrev_b32_e32 v13, 1, v13
	v_lshlrev_b32_e32 v30, 7, v29
	v_lshrrev_b32_e32 v29, 1, v29
	v_lshlrev_b32_e32 v33, 7, v32
	v_lshrrev_b32_e32 v32, 1, v32
	v_lshlrev_b32_e32 v36, 7, v35
	v_lshrrev_b32_e32 v35, 1, v35
	v_lshlrev_b32_e32 v39, 7, v38
	v_lshrrev_b32_e32 v38, 1, v38
	v_lshlrev_b32_e32 v41, 7, v22
	v_lshrrev_b32_e32 v22, 1, v22
	v_bitop3_b32 v28, v13, v8, 3 bitop3:0x6c
	v_bitop3_b32 v31, v29, v8, 3 bitop3:0x6c
	v_bitop3_b32 v34, v32, v8, 6 bitop3:0x6c
	v_bitop3_b32 v37, v35, v8, 6 bitop3:0x6c
	v_bitop3_b32 v40, v38, v8, 7 bitop3:0x6c
	v_bitop3_b32 v8, v22, v8, 7 bitop3:0x6c
	v_xor_b32_e32 v43, v149, v3
	v_lshl_add_u32 v42, v8, 4, v41
	v_lshlrev_b32_e32 v8, 8, v149
	v_lshlrev_b32_e32 v43, 4, v43
	s_add_u32 s8, s70, s17
	v_and_or_b32 v173, v43, s84, v8
	v_ashrrev_i32_e32 v8, 7, v23
	s_addc_u32 s9, s71, 0
	v_lshl_add_u64 v[154:155], v[4:5], 0, v[10:11]
	s_lshl_b32 s88, s12, 13
	v_lshlrev_b32_e32 v4, 5, v3
	v_lshlrev_b32_e32 v5, 2, v21
	s_movk_i32 s12, 0xffc0
	v_xor_b32_e32 v12, v12, v8
	s_nop 0
	v_lshl_add_u32 v43, v12, 4, v9
	v_bitop3_b32 v9, v13, v8, 3 bitop3:0x6c
	v_add_u32_e32 v176, 0x16000, v4
	v_and_b32_e32 v4, 1, v17
	v_lshl_add_u32 v28, v28, 4, v27
	v_lshl_add_u32 v27, v9, 4, v27
	v_bitop3_b32 v9, v29, v8, 3 bitop3:0x6c
	v_cmp_eq_u32_e32 vcc, 1, v4
	v_lshl_add_u32 v29, v9, 4, v30
	v_bitop3_b32 v9, v32, v8, 6 bitop3:0x6c
	s_xor_b64 s[78:79], vcc, -1
	s_lshl_b32 s11, s11, 9
	v_lshl_add_u32 v31, v31, 4, v30
	v_lshl_add_u32 v30, v9, 4, v33
	v_bitop3_b32 v9, v35, v8, 6 bitop3:0x6c
	s_add_u32 s11, s13, s11
	v_and_b32_e32 v18, 31, v3
	v_lshl_add_u32 v32, v9, 4, v36
	v_bitop3_b32 v9, v38, v8, 7 bitop3:0x6c
	v_lshl_add_u64 v[146:147], s[8:9], 0, v[0:1]
	v_lshlrev_b32_e32 v0, 5, v14
	s_addc_u32 s12, s14, 0
	s_lshl_b32 s10, s10, 1
	v_lshrrev_b32_e32 v2, 5, v3
	v_bfe_u32 v19, v3, 5, 1
	v_bfe_u32 v20, v3, 1, 3
	v_lshl_add_u32 v34, v34, 4, v33
	v_lshl_add_u32 v33, v9, 4, v39
	v_xor_b32_e32 v9, v172, v3
	v_and_b32_e32 v35, 0xffffff80, v24
	v_bitop3_b32 v24, v24, s51, v3 bitop3:0x48
	v_cmp_gt_i32_e64 s[6:7], 16, v3
	v_lshl_add_u64 v[152:153], v[6:7], 0, v[10:11]
	v_and_b32_e32 v0, 0x60, v0
	v_lshlrev_b32_e32 v177, 8, v18
	v_and_b32_e32 v6, 15, v3
	v_lshlrev_b32_e32 v3, 1, v3
	s_add_u32 s10, s11, s10
	v_lshl_or_b32 v179, v16, 13, v177
	v_lshl_or_b32 v7, v16, 5, v18
	v_and_b32_e32 v16, 14, v3
	v_or_b32_e32 v3, v0, v18
	s_addc_u32 s11, s12, 0
	v_lshlrev_b32_e32 v0, 1, v0
	v_lshl_add_u64 v[4:5], s[10:11], 0, v[0:1]
	v_lshlrev_b32_e32 v0, 1, v18
	v_lshl_add_u64 v[4:5], v[4:5], 0, v[0:1]
	v_bitop3_b32 v0, v2, v6, 1 bitop3:0x6c
	v_lshlrev_b32_e32 v184, 4, v0
	v_bitop3_b32 v0, v19, v6, 2 bitop3:0x36
	v_lshlrev_b32_e32 v185, 4, v0
	v_bitop3_b32 v0, v19, v6, 4 bitop3:0x36
	v_lshlrev_b32_e32 v186, 4, v0
	v_bitop3_b32 v0, v19, v6, 6 bitop3:0x36
	v_lshlrev_b32_e32 v187, 4, v0
	v_bitop3_b32 v0, v19, v6, 8 bitop3:0x36
	v_bitop3_b32 v8, v22, v8, 7 bitop3:0x6c
	v_lshlrev_b32_e32 v188, 4, v0
	v_bitop3_b32 v0, v19, v6, 10 bitop3:0x36
	v_lshl_add_u32 v22, v8, 4, v41
	v_lshlrev_b32_e32 v8, 8, v172
	v_lshlrev_b32_e32 v9, 4, v9
	v_lshlrev_b32_e32 v189, 4, v0
	v_bitop3_b32 v0, v19, v6, 12 bitop3:0x36
	v_and_or_b32 v174, v9, s84, v8
	v_lshlrev_b32_e32 v8, 2, v19
	v_lshlrev_b32_e32 v190, 4, v0
	v_bitop3_b32 v0, v19, v6, 14 bitop3:0x36
	v_lshlrev_b32_e32 v191, 4, v0
	v_lshl_or_b32 v0, v15, 5, v8
	v_cmp_le_u32_e32 vcc, v7, v0
	v_lshlrev_b32_e32 v180, 7, v3
	v_lshrrev_b32_e32 v9, 3, v7
	v_cndmask_b32_e64 v3, 0, 1, vcc
	v_cmp_ge_u32_e32 vcc, v7, v0
	v_lshlrev_b32_e32 v8, 4, v9
	v_lshlrev_b32_e32 v181, 7, v18
	v_cndmask_b32_e64 v6, 0, 1, vcc
	v_cndmask_b32_e64 v3, v6, v3, s[4:5]
	v_and_b32_e32 v3, 1, v3
	v_cmp_eq_u32_e64 s[10:11], 1, v3
	v_lshlrev_b32_e32 v3, 7, v0
	v_lshlrev_b32_e32 v6, 5, v19
	v_bitop3_b32 v3, v3, v8, v6 bitop3:0xf6
	v_add_u32_e32 v17, 0x14000, v3
	v_or_b32_e32 v3, 1, v0
	v_cmp_gt_u32_e32 vcc, v7, v0
	v_lshl_add_u32 v37, v37, 4, v36
	v_lshl_add_u32 v40, v40, 4, v39
	v_cndmask_b32_e64 v10, 0, 1, vcc
	v_cmp_le_u32_e32 vcc, v7, v3
	v_lshlrev_b32_e32 v3, 7, v3
	v_bitop3_b32 v3, v3, v8, v6 bitop3:0xf6
	v_cndmask_b32_e64 v11, 0, 1, vcc
	v_cndmask_b32_e64 v10, v10, v11, s[4:5]
	v_add_u32_e32 v18, 0x14000, v3
	v_or_b32_e32 v3, 2, v0
	v_and_b32_e32 v10, 1, v10
	v_cmp_le_u32_e32 vcc, v7, v3
	v_cmp_eq_u32_e64 s[12:13], 1, v10
	v_lshlrev_b32_e32 v23, 1, v172
	v_cndmask_b32_e64 v10, 0, 1, vcc
	v_cmp_ge_u32_e32 vcc, v7, v3
	v_and_b32_e32 v23, 14, v23
	v_cmp_gt_i32_e64 s[8:9], 4, v14
	v_cndmask_b32_e64 v11, 0, 1, vcc
	v_cndmask_b32_e64 v10, v11, v10, s[4:5]
	v_and_b32_e32 v10, 1, v10
	v_cmp_eq_u32_e64 s[14:15], 1, v10
	v_lshrrev_b32_e32 v10, 1, v3
	v_bitop3_b32 v10, v10, v9, 3 bitop3:0x6c
	v_lshlrev_b32_e32 v10, 4, v10
	v_lshl_or_b32 v3, v3, 7, v10
	v_add_u32_e32 v21, 0x14000, v3
	v_or_b32_e32 v3, 3, v0
	v_cmp_le_u32_e32 vcc, v7, v3
	v_lshl_or_b32 v178, v15, 13, v177
	v_mov_b32_e32 v14, v1
	v_cndmask_b32_e64 v10, 0, 1, vcc
	v_cmp_ge_u32_e32 vcc, v7, v3
	v_mov_b32_e32 v15, v1
	v_lshl_or_b32 v183, v19, 4, v137
	v_cndmask_b32_e64 v11, 0, 1, vcc
	v_cndmask_b32_e64 v10, v11, v10, s[4:5]
	v_and_b32_e32 v10, 1, v10
	v_cmp_eq_u32_e64 s[16:17], 1, v10
	v_lshrrev_b32_e32 v10, 1, v3
	v_bitop3_b32 v10, v10, v9, 3 bitop3:0x6c
	v_lshlrev_b32_e32 v10, 4, v10
	v_lshl_or_b32 v3, v3, 7, v10
	v_add_u32_e32 v36, 0x14000, v3
	v_or_b32_e32 v3, 8, v0
	v_cmp_le_u32_e32 vcc, v7, v3
	v_mov_b32_e32 v12, v1
	v_mov_b32_e32 v13, v1
	v_cndmask_b32_e64 v10, 0, 1, vcc
	v_cmp_ge_u32_e32 vcc, v7, v3
	v_add_u32_e32 v197, v26, v25
	v_add_u32_e32 v198, v28, v25
	v_cndmask_b32_e64 v11, 0, 1, vcc
	v_cndmask_b32_e64 v10, v11, v10, s[4:5]
	v_and_b32_e32 v10, 1, v10
	v_cmp_eq_u32_e64 s[18:19], 1, v10
	v_lshrrev_b32_e32 v10, 1, v3
	v_bitop3_b32 v10, v10, v9, 6 bitop3:0x6c
	v_lshlrev_b32_e32 v10, 4, v10
	v_lshl_or_b32 v3, v3, 7, v10
	v_add_u32_e32 v38, 0x14000, v3
	v_or_b32_e32 v3, 9, v0
	v_cmp_le_u32_e32 vcc, v7, v3
	v_add_u32_e32 v199, v31, v25
	v_add_u32_e32 v200, v34, v25
	v_cndmask_b32_e64 v10, 0, 1, vcc
	v_cmp_ge_u32_e32 vcc, v7, v3
	v_add_u32_e32 v201, v37, v25
	v_add_u32_e32 v202, v40, v25
	v_cndmask_b32_e64 v11, 0, 1, vcc
	v_cndmask_b32_e64 v10, v11, v10, s[4:5]
	v_and_b32_e32 v10, 1, v10
	v_cmp_eq_u32_e64 s[20:21], 1, v10
	v_lshrrev_b32_e32 v10, 1, v3
	v_bitop3_b32 v10, v10, v9, 6 bitop3:0x6c
	v_lshlrev_b32_e32 v10, 4, v10
	v_lshl_or_b32 v3, v3, 7, v10
	v_add_u32_e32 v39, 0x14000, v3
	v_or_b32_e32 v3, 10, v0
	v_cmp_le_u32_e32 vcc, v7, v3
	v_add_u32_e32 v203, v42, v25
	v_add_u32_e32 v204, v43, v23
	v_cndmask_b32_e64 v10, 0, 1, vcc
	v_cmp_ge_u32_e32 vcc, v7, v3
	v_add_u32_e32 v205, v27, v23
	v_add_u32_e32 v206, v29, v23
	v_cndmask_b32_e64 v11, 0, 1, vcc
	v_cndmask_b32_e64 v10, v11, v10, s[4:5]
	v_and_b32_e32 v10, 1, v10
	v_cmp_eq_u32_e64 s[22:23], 1, v10
	v_lshrrev_b32_e32 v10, 1, v3
	v_bitop3_b32 v10, v10, v9, 7 bitop3:0x6c
	v_lshlrev_b32_e32 v10, 4, v10
	v_lshl_or_b32 v3, v3, 7, v10
	v_add_u32_e32 v41, 0x14000, v3
	v_or_b32_e32 v3, 11, v0
	v_cmp_le_u32_e32 vcc, v7, v3
	v_add_u32_e32 v207, v30, v23
	v_add_u32_e32 v208, v32, v23
	v_cndmask_b32_e64 v10, 0, 1, vcc
	v_cmp_ge_u32_e32 vcc, v7, v3
	v_add_u32_e32 v209, v33, v23
	v_add_u32_e32 v210, v22, v23
	v_cndmask_b32_e64 v11, 0, 1, vcc
	v_cndmask_b32_e64 v10, v11, v10, s[4:5]
	v_and_b32_e32 v10, 1, v10
	v_cmp_eq_u32_e64 s[24:25], 1, v10
	v_lshrrev_b32_e32 v10, 1, v3
	v_bitop3_b32 v10, v10, v9, 7 bitop3:0x6c
	v_lshlrev_b32_e32 v10, 4, v10
	v_lshl_or_b32 v3, v3, 7, v10
	v_add_u32_e32 v44, 0x14000, v3
	v_or_b32_e32 v3, 16, v0
	v_cmp_le_u32_e32 vcc, v7, v3
	v_add_u32_e32 v211, v35, v24
	v_add_u32_e32 v212, v17, v16
	v_cndmask_b32_e64 v10, 0, 1, vcc
	v_cmp_ge_u32_e32 vcc, v7, v3
	v_lshlrev_b32_e32 v3, 7, v3
	v_bitop3_b32 v3, v3, v8, v6 bitop3:0xf6
	v_cndmask_b32_e64 v11, 0, 1, vcc
	v_cndmask_b32_e64 v10, v11, v10, s[4:5]
	v_add_u32_e32 v45, 0x14000, v3
	v_or_b32_e32 v3, 17, v0
	v_and_b32_e32 v10, 1, v10
	v_cmp_le_u32_e32 vcc, v7, v3
	v_cmp_eq_u32_e64 s[26:27], 1, v10
	v_add_u32_e32 v213, v18, v16
	v_cndmask_b32_e64 v10, 0, 1, vcc
	v_cmp_ge_u32_e32 vcc, v7, v3
	v_lshlrev_b32_e32 v3, 7, v3
	v_bitop3_b32 v3, v3, v8, v6 bitop3:0xf6
	v_add_u32_e32 v46, 0x14000, v3
	v_or_b32_e32 v3, 18, v0
	v_cndmask_b32_e64 v11, 0, 1, vcc
	v_cmp_le_u32_e32 vcc, v7, v3
	v_cndmask_b32_e64 v10, v11, v10, s[4:5]
	v_and_b32_e32 v10, 1, v10
	v_cndmask_b32_e64 v6, 0, 1, vcc
	v_cmp_ge_u32_e32 vcc, v7, v3
	v_cmp_eq_u32_e64 s[28:29], 1, v10
	v_mov_b32_e32 v10, v1
	v_cndmask_b32_e64 v8, 0, 1, vcc
	v_cndmask_b32_e64 v6, v8, v6, s[4:5]
	v_and_b32_e32 v6, 1, v6
	v_cmp_eq_u32_e64 s[30:31], 1, v6
	v_lshrrev_b32_e32 v6, 1, v3
	v_bitop3_b32 v6, v6, v9, 3 bitop3:0x6c
	v_lshlrev_b32_e32 v6, 4, v6
	v_lshl_or_b32 v3, v3, 7, v6
	v_add_u32_e32 v47, 0x14000, v3
	v_or_b32_e32 v3, 19, v0
	v_cmp_le_u32_e32 vcc, v7, v3
	v_mov_b32_e32 v11, v1
	v_add_u32_e32 v214, v21, v16
	v_cndmask_b32_e64 v6, 0, 1, vcc
	v_cmp_ge_u32_e32 vcc, v7, v3
	v_add_u32_e32 v215, v36, v16
	v_add_u32_e32 v216, v38, v16
	v_cndmask_b32_e64 v8, 0, 1, vcc
	v_cndmask_b32_e64 v6, v8, v6, s[4:5]
	v_and_b32_e32 v6, 1, v6
	v_cmp_eq_u32_e64 s[34:35], 1, v6
	v_lshrrev_b32_e32 v6, 1, v3
	v_bitop3_b32 v6, v6, v9, 3 bitop3:0x6c
	v_lshlrev_b32_e32 v6, 4, v6
	v_lshl_or_b32 v3, v3, 7, v6
	v_add_u32_e32 v48, 0x14000, v3
	v_or_b32_e32 v3, 24, v0
	v_cmp_le_u32_e32 vcc, v7, v3
	v_add_u32_e32 v217, v39, v16
	v_add_u32_e32 v218, v41, v16
	v_cndmask_b32_e64 v6, 0, 1, vcc
	v_cmp_ge_u32_e32 vcc, v7, v3
	v_add_u32_e32 v219, v44, v16
	v_add_u32_e32 v220, v45, v16
	v_cndmask_b32_e64 v8, 0, 1, vcc
	v_cndmask_b32_e64 v6, v8, v6, s[4:5]
	v_and_b32_e32 v6, 1, v6
	v_cmp_eq_u32_e64 s[36:37], 1, v6
	v_lshrrev_b32_e32 v6, 1, v3
	v_bitop3_b32 v6, v6, v9, 6 bitop3:0x6c
	v_lshlrev_b32_e32 v6, 4, v6
	v_lshl_or_b32 v3, v3, 7, v6
	v_add_u32_e32 v49, 0x14000, v3
	v_or_b32_e32 v3, 25, v0
	v_cmp_le_u32_e32 vcc, v7, v3
	v_add_u32_e32 v221, v46, v16
	v_add_u32_e32 v222, v47, v16
	v_cndmask_b32_e64 v6, 0, 1, vcc
	v_cmp_ge_u32_e32 vcc, v7, v3
	v_add_u32_e32 v223, v48, v16
	v_add_u32_e32 v224, v49, v16
	v_cndmask_b32_e64 v8, 0, 1, vcc
	v_cndmask_b32_e64 v6, v8, v6, s[4:5]
	v_and_b32_e32 v6, 1, v6
	v_cmp_eq_u32_e64 s[38:39], 1, v6
	v_lshrrev_b32_e32 v6, 1, v3
	v_bitop3_b32 v6, v6, v9, 6 bitop3:0x6c
	v_lshlrev_b32_e32 v6, 4, v6
	v_lshl_or_b32 v3, v3, 7, v6
	v_add_u32_e32 v50, 0x14000, v3
	v_or_b32_e32 v3, 26, v0
	v_cmp_le_u32_e32 vcc, v7, v3
	v_or_b32_e32 v0, 27, v0
	v_add_u32_e32 v225, v50, v16
	v_cndmask_b32_e64 v6, 0, 1, vcc
	v_cmp_ge_u32_e32 vcc, v7, v3
	v_or_b32_e32 v182, 0x14000, v181
	s_waitcnt vmcnt(16)
	v_mov_b64_e32 v[170:171], 0
	v_cndmask_b32_e64 v8, 0, 1, vcc
	v_cndmask_b32_e64 v6, v8, v6, s[4:5]
	v_and_b32_e32 v6, 1, v6
	v_cmp_eq_u32_e64 s[40:41], 1, v6
	v_lshrrev_b32_e32 v6, 1, v3
	v_bitop3_b32 v6, v6, v9, 7 bitop3:0x6c
	v_lshlrev_b32_e32 v6, 4, v6
	v_lshl_or_b32 v3, v3, 7, v6
	v_cmp_le_u32_e32 vcc, v7, v0
	v_add_u32_e32 v51, 0x14000, v3
	v_mov_b32_e32 v8, v1
	v_cndmask_b32_e64 v3, 0, 1, vcc
	v_cmp_ge_u32_e32 vcc, v7, v0
	v_mov_b32_e32 v7, v1
	v_add_u32_e32 v226, v51, v16
	v_cndmask_b32_e64 v6, 0, 1, vcc
	v_cndmask_b32_e64 v3, v6, v3, s[4:5]
	v_and_b32_e32 v3, 1, v3
	v_cmp_eq_u32_e64 s[42:43], 1, v3
	v_lshrrev_b32_e32 v3, 1, v0
	v_bitop3_b32 v3, v3, v9, 7 bitop3:0x6c
	v_lshlrev_b32_e32 v3, 4, v3
	v_lshl_or_b32 v0, v0, 7, v3
	v_add_u32_e32 v52, 0x14000, v0
	v_bitop3_b32 v0, v2, v20, 1 bitop3:0x6c
	v_lshlrev_b32_e32 v192, 4, v0
	v_bitop3_b32 v0, v19, v20, 2 bitop3:0x36
	v_lshlrev_b32_e32 v193, 4, v0
	v_bitop3_b32 v0, v19, v20, 4 bitop3:0x36
	v_lshlrev_b32_e32 v195, 4, v0
	v_bitop3_b32 v0, v19, v20, 6 bitop3:0x36
	v_lshlrev_b32_e32 v196, 4, v0
	v_lshlrev_b32_e32 v0, 13, v19
	v_lshl_add_u64 v[168:169], v[4:5], 0, v[0:1]
	v_mov_b32_e32 v0, v1
	v_mov_b32_e32 v2, v1
	v_mov_b32_e32 v3, v1
	v_mov_b32_e32 v4, v1
	v_mov_b32_e32 v5, v1
	v_mov_b32_e32 v6, v1
	v_mov_b32_e32 v9, v1
	v_add_u32_e32 v227, v52, v16
	v_mov_b64_e32 v[30:31], v[14:15]
	v_mov_b64_e32 v[46:47], v[14:15]
	v_mov_b64_e32 v[62:63], v[14:15]
	v_mov_b64_e32 v[78:79], v[14:15]
	s_movk_i32 s89, 0x82
	v_mov_b64_e32 v[28:29], v[12:13]
	v_mov_b64_e32 v[26:27], v[10:11]
	v_mov_b64_e32 v[24:25], v[8:9]
	v_mov_b64_e32 v[22:23], v[6:7]
	v_mov_b64_e32 v[20:21], v[4:5]
	v_mov_b64_e32 v[18:19], v[2:3]
	v_mov_b64_e32 v[16:17], v[0:1]
	v_mov_b64_e32 v[44:45], v[12:13]
	v_mov_b64_e32 v[42:43], v[10:11]
	v_mov_b64_e32 v[40:41], v[8:9]
	v_mov_b64_e32 v[38:39], v[6:7]
	v_mov_b64_e32 v[36:37], v[4:5]
	v_mov_b64_e32 v[34:35], v[2:3]
	v_mov_b64_e32 v[32:33], v[0:1]
	v_mov_b64_e32 v[60:61], v[12:13]
	v_mov_b64_e32 v[58:59], v[10:11]
	v_mov_b64_e32 v[56:57], v[8:9]
	v_mov_b64_e32 v[54:55], v[6:7]
	v_mov_b64_e32 v[52:53], v[4:5]
	v_mov_b64_e32 v[50:51], v[2:3]
	v_mov_b64_e32 v[48:49], v[0:1]
	v_mov_b64_e32 v[76:77], v[12:13]
	v_mov_b64_e32 v[74:75], v[10:11]
	v_mov_b64_e32 v[72:73], v[8:9]
	v_mov_b64_e32 v[70:71], v[6:7]
	v_mov_b64_e32 v[68:69], v[4:5]
	v_mov_b64_e32 v[66:67], v[2:3]
	v_mov_b64_e32 v[64:65], v[0:1]
	s_mov_b32 s81, s49
	v_mov_b64_e32 v[6:7], 0
	v_mov_b64_e32 v[8:9], 0
	v_mov_b64_e32 v[10:11], 0
	v_and_b32_e32 v113, 15, v148
	v_bfe_u32 v114, v148, 5, 1
	v_lshlrev_b32_e32 v115, 2, v113
	v_and_b32_e32 v115, 12, v115
	v_lshrrev_b32_e32 v116, 2, v113
	v_or_b32_e32 v115, v115, v116
	v_xor_b32_e32 v115, v115, v114
	v_xor_b32_e32 v116, 0, v115
	v_lshlrev_b32_e32 v184, 4, v116
	v_xor_b32_e32 v116, 2, v115
	v_lshlrev_b32_e32 v185, 4, v116
	v_xor_b32_e32 v116, 4, v115
	v_lshlrev_b32_e32 v186, 4, v116
	v_xor_b32_e32 v116, 6, v115
	v_lshlrev_b32_e32 v187, 4, v116
	v_xor_b32_e32 v116, 8, v115
	v_lshlrev_b32_e32 v188, 4, v116
	v_xor_b32_e32 v116, 10, v115
	v_lshlrev_b32_e32 v189, 4, v116
	v_xor_b32_e32 v116, 12, v115
	v_lshlrev_b32_e32 v190, 4, v116
	v_xor_b32_e32 v116, 14, v115
	v_lshlrev_b32_e32 v191, 4, v116
	v_lshlrev_b32_e32 v116, 2, v149
	v_and_b32_e32 v116, 12, v116
	v_bfe_u32 v117, v149, 2, 2
	v_or_b32_e32 v116, v116, v117
	v_and_b32_e32 v117, 14, v113
	v_xor_b32_e32 v116, v116, v117
	v_lshlrev_b32_e32 v116, 4, v116
	v_lshl_or_b32 v173, v149, 8, v116
	v_and_b32_e32 v117, 1, v113
	v_lshl_or_b32 v173, v117, 3, v173
	v_xor_b32_e32 v174, 16, v173
	v_mov_b64_e32 v[232:233], 0
	v_mov_b64_e32 v[234:235], 0
	v_and_b32_e32 v116, 3, v148
	v_bfe_u32 v117, v148, 2, 2
	v_bfe_u32 v118, v148, 4, 1
	v_and_b32_e32 v119, 1, v116
	v_lshl_or_b32 v119, v118, 1, v119
	v_lshlrev_b32_e32 v120, 1, v114
	v_xor_b32_e32 v119, v119, v120
	v_lshl_or_b32 v119, v117, 2, v119
	v_lshlrev_b32_e32 v119, 4, v119
	v_lshrrev_b32_e32 v120, 1, v116
	v_lshl_or_b32 v119, v120, 3, v119
	v_lshl_add_u32 v120, v114, 3, v117
	v_lshl_or_b32 v119, v120, 8, v119
	v_add_u32_e32 v197, 0x4000, v119
	v_xor_b32_e32 v198, 64, v197
	v_xor_b32_e32 v199, 0x80, v197
	v_xor_b32_e32 v200, 0xc0, v197
	v_xor_b32_e32 v201, 16, v197
	v_xor_b32_e32 v202, 16, v198
	v_xor_b32_e32 v203, 16, v199
	v_xor_b32_e32 v204, 16, v200
	v_add_u32_e32 v182, 0x4000, v182
	v_add_u32_e32 v176, 0x2000, v176
	v_add_u32_e32 v183, 0x4000, v183
	v_add_u32_e32 v212, 0x4000, v212
	v_add_u32_e32 v213, 0x4000, v213
	v_add_u32_e32 v214, 0x4000, v214
	v_add_u32_e32 v215, 0x4000, v215
	v_add_u32_e32 v216, 0x4000, v216
	v_add_u32_e32 v217, 0x4000, v217
	v_add_u32_e32 v218, 0x4000, v218
	v_add_u32_e32 v219, 0x4000, v219
	v_add_u32_e32 v220, 0x4000, v220
	v_add_u32_e32 v221, 0x4000, v221
	v_add_u32_e32 v222, 0x4000, v222
	v_add_u32_e32 v223, 0x4000, v223
	v_add_u32_e32 v224, 0x4000, v224
	v_add_u32_e32 v225, 0x4000, v225
	v_add_u32_e32 v226, 0x4000, v226
	v_add_u32_e32 v227, 0x4000, v227
	s_cmp_lg_u64 s[8:9], 0
	s_cbranch_scc0 .Lscan_noprio
	s_setprio 3
.Lscan_noprio:
	v_and_b32_e32 v116, 0x1f0, v148
	v_cmp_eq_u32_e32 vcc, 0x100, v116
	s_mov_b64 s[6:7], vcc
	s_branch .LBB0_1146
